# P6 epilogue operands (conv weights/bias, row sums) LDS-DMA-prefetched into spare LDS during the tile's K-loop; epilogue no longer drains vmcnt(0) at its head
# speedup vs baseline: 1.0074x; 1.0074x over previous
;     __device__ __forceinline__ void operator()(EPI_ARGS) const {
;         const int f0 = u.pn * 128 + wc * 32 + 8 * fq;
;         const int lane = fq * 16 + fr, src1 = (lane & 48) | ((fr - 1) & 15), src2 = (lane & 48) | ((fr - 2) & 15);
;         f32x4 w0[2], w1[2], w2[2], bb[2];
; #pragma unroll
;         for (int n = 0; n < 2; ++n) { w0[n] = *(const f32x4*)(cw + f0 + 4 * n); w1[n] = *(const f32x4*)(cw + FF + f0 + 4 * n); w2[n] = *(const f32x4*)(cw + 2 * FF + f0 + 4 * n); bb[n] = *(const f32x4*)(cb + f0 + 4 * n); }
;         float rsv[2][4];
; #pragma unroll
;         for (int ai = 0; ai < 2; ++ai)
; #pragma unroll
;             for (int m = 0; m < 4; ++m) rsv[ai][m] = ss2[ROW_OF(ai, m)];
.LBB0_923:
	v_readfirstlane_b32 s76, v212
	s_lshr_b32 s76, s76, 6
	s_xor_b32 s76, s76, 4
	s_or_b32 s77, s76, s62
	s_cmp_lg_u32 s77, 0
	s_cbranch_scc1 .Lp6pf_skip
	v_and_b32_e32 v240, 63, v212
	v_and_b32_e32 v241, 31, v240
	v_lshlrev_b32_e32 v241, 4, v241
	s_lshl_b32 s77, s9, 9
	v_add_u32_e32 v242, s77, v241
	v_mov_b32_e32 v243, 0
	v_cmp_lt_u32_e32 vcc, 31, v240
	v_mov_b32_e32 v244, s84
	v_mov_b32_e32 v245, s85
	v_mov_b32_e32 v246, s16
	v_mov_b32_e32 v247, s17
	v_cndmask_b32_e32 v244, v244, v246, vcc
	v_cndmask_b32_e32 v245, v245, v247, vcc
	v_lshl_add_u64 v[244:245], v[244:245], 0, v[242:243]
	s_mov_b32 m0, 0x20400
	s_nop 0
	global_load_lds_dwordx4 v[244:245], off
	v_mov_b32_e32 v244, s18
	v_mov_b32_e32 v245, s19
	v_mov_b32_e32 v246, s86
	v_mov_b32_e32 v247, s87
	v_cndmask_b32_e32 v244, v244, v246, vcc
	v_cndmask_b32_e32 v245, v245, v247, vcc
	v_lshl_add_u64 v[244:245], v[244:245], 0, v[242:243]
	s_mov_b32 m0, 0x20800
	s_nop 0
	global_load_lds_dwordx4 v[244:245], off
	v_lshlrev_b32_e32 v242, 4, v240
	s_lshl_b32 s77, s8, 10
	v_add_u32_e32 v242, s77, v242
	v_mov_b32_e32 v244, s68
	v_mov_b32_e32 v245, s69
	v_lshl_add_u64 v[244:245], v[244:245], 0, v[242:243]
	s_mov_b32 m0, 0x20c00
	s_nop 0
	global_load_lds_dwordx4 v[244:245], off

;     __device__ __forceinline__ void operator()(EPI_ARGS) const {
;         const int f0 = u.pn * 128 + wc * 32 + 8 * fq;
;         const int lane = fq * 16 + fr, src1 = (lane & 48) | ((fr - 1) & 15), src2 = (lane & 48) | ((fr - 2) & 15);
;         f32x4 w0[2], w1[2], w2[2], bb[2];
; #pragma unroll
;         for (int n = 0; n < 2; ++n) { w0[n] = *(const f32x4*)(cw + f0 + 4 * n); w1[n] = *(const f32x4*)(cw + FF + f0 + 4 * n); w2[n] = *(const f32x4*)(cw + 2 * FF + f0 + 4 * n); bb[n] = *(const f32x4*)(cb + f0 + 4 * n); }
;         float rsv[2][4];
; #pragma unroll
;         for (int ai = 0; ai < 2; ++ai)
; #pragma unroll
;             for (int m = 0; m < 4; ++m) rsv[ai][m] = ss2[ROW_OF(ai, m)];
; #pragma unroll
;         for (int ai = 0; ai < 2; ++ai) {
;             const int blk = u.pm * 4 + ai * 2 + wr;
;             f32x4 q1[2], q2[2];
; #pragma unroll
;             for (int n = 0; n < 2; ++n) { q1[n] = (f32x4){0.f, 0.f, 0.f, 0.f}; q2[n] = (f32x4){0.f, 0.f, 0.f, 0.f}; }
; #pragma unroll
;             for (int m = 0; m < 4; ++m) {
;                 const int row = ROW_OF(ai, m);
;                 const float rs = __builtin_amdgcn_rsqf(rsv[ai][m] * (1.0f / D) + EPS);
;                 f32x4 o[2];
; #pragma unroll
;                 for (int n = 0; n < 2; ++n) {
;                     const f32x4 gv = acc[ai][0][m][n] * rs, vv = acc[ai][1][m][n] * rs;
.LBB0_926:
	s_lshl_b32 s0, s9, 7
	v_mov_b32_e32 v184, v206
	v_mov_b32_e32 v168, v207
	v_lshl_add_u32 v238, v207, 3, s35
	v_add_u32_e32 v239, s34, v206
	v_lshlrev_b32_e32 v238, 2, v238
	v_lshlrev_b32_e32 v239, 2, v239
	v_add_u32_e32 v238, 0x20400, v238
	v_add_u32_e32 v239, 0x20c00, v239
	s_or_b32 s0, s0, s35
	s_nop 0
	v_lshl_add_u32 v174, v168, 3, s0
	s_lshl_b32 s0, s8, 8
	s_add_i32 s0, s0, s34
	v_ashrrev_i32_e32 v175, 31, v174
	v_add_u32_e32 v192, s0, v184
	v_lshlrev_b64 v[64:65], 2, v[174:175]
	v_ashrrev_i32_e32 v193, 31, v192
	v_lshl_add_u64 v[66:67], s[84:85], 0, v[64:65]
	v_lshl_add_u64 v[68:69], s[16:17], 0, v[64:65]
	v_lshl_add_u64 v[70:71], s[18:19], 0, v[64:65]
	v_lshl_add_u64 v[76:77], s[86:87], 0, v[64:65]
	v_lshl_add_u64 v[176:177], v[192:193], 2, s[68:69]
	ds_read_b128 v[92:95], v238 offset:16
	ds_read_b128 v[72:75], v238
	ds_read_b128 v[84:87], v238 offset:528
	s_nop 0
	ds_read_b128 v[64:67], v238 offset:512
	ds_read_b128 v[88:91], v238 offset:1040
	s_nop 0
	ds_read_b128 v[68:71], v238 offset:1024
	s_nop 0
	ds_read_b128 v[96:99], v238 offset:1552
	s_nop 0
	ds_read_b128 v[76:79], v238 offset:1536
	v_add_u32_e32 v190, 16, v192
	ds_read_b32 v220, v239
	v_ashrrev_i32_e32 v191, 31, v190
	v_add_u32_e32 v188, 32, v192
	v_add_u32_e32 v186, 48, v192
	v_add_u32_e32 v182, 0x80, v192
	v_add_u32_e32 v180, 0x90, v192
	v_add_u32_e32 v178, 0xa0, v192
	v_add_u32_e32 v176, 0xb0, v192
	v_lshl_add_u64 v[194:195], v[190:191], 2, s[68:69]
	v_ashrrev_i32_e32 v189, 31, v188
	v_ashrrev_i32_e32 v187, 31, v186
	v_ashrrev_i32_e32 v183, 31, v182
	v_ashrrev_i32_e32 v181, 31, v180
	v_ashrrev_i32_e32 v179, 31, v178
	v_ashrrev_i32_e32 v177, 31, v176
	v_lshl_add_u64 v[196:197], v[188:189], 2, s[68:69]
	v_lshl_add_u64 v[198:199], v[186:187], 2, s[68:69]
	v_lshl_add_u64 v[200:201], v[182:183], 2, s[68:69]
	v_lshl_add_u64 v[202:203], v[180:181], 2, s[68:69]
	v_lshl_add_u64 v[204:205], v[178:179], 2, s[68:69]
	v_lshl_add_u64 v[218:219], v[176:177], 2, s[68:69]
	ds_read_b32 v217, v239 offset:64
	ds_read_b32 v193, v239 offset:128
	ds_read_b32 v191, v239 offset:192
	ds_read_b32 v189, v239 offset:512
	ds_read_b32 v187, v239 offset:576
	ds_read_b32 v183, v239 offset:640
	ds_read_b32 v181, v239 offset:704
	v_lshl_add_u32 v168, v168, 4, v184
	v_add_u32_e32 v177, -1, v184
	v_add_u32_e32 v179, 14, v184
	v_and_b32_e32 v177, 15, v177
	v_and_b32_e32 v179, 15, v179
	v_and_b32_e32 v168, 48, v168
	v_or3_b32 v177, v168, v177, v214
	v_or3_b32 v168, v168, v179, v214
	s_lshl_b32 s0, s8, 2
	s_add_i32 s60, s0, s29
	s_ashr_i32 s61, s60, 31
	v_lshlrev_b32_e32 v177, 2, v177
	v_ashrrev_i32_e32 v185, 31, v184
	s_lshl_b64 s[62:63], s[60:61], 1
	v_lshl_add_u64 v[194:195], s[62:63], 0, v[184:185]
	v_mad_u64_u32 v[196:197], s[0:1], v194, s65, v[174:175]
	v_mad_i32_i24 v197, v195, s65, v197
	v_cmp_lt_i32_e64 s[6:7], 1, v184
	v_cmp_gt_i32_e64 s[8:9], 2, v184
	v_lshlrev_b64 v[202:203], 2, v[196:197]
	s_waitcnt lgkmcnt(0)
	v_fmamk_f32 v179, v220, 0x3a000000, v215
	v_rsq_f32_e32 v204, v179
	v_lshlrev_b32_e32 v179, 2, v168
	v_pk_mul_f32 v[158:159], v[158:159], v[204:205] op_sel_hi:[1,0]
	v_pk_mul_f32 v[156:157], v[156:157], v[204:205] op_sel_hi:[1,0]
	s_nop 1
	v_mov_b32_dpp v218, v156 row_ror:1 row_mask:0xf bank_mask:0xf
	v_mov_b32_dpp v219, v156 row_ror:2 row_mask:0xf bank_mask:0xf
	v_mov_b32_dpp v220, v157 row_ror:1 row_mask:0xf bank_mask:0xf
	v_mov_b32_dpp v221, v157 row_ror:2 row_mask:0xf bank_mask:0xf
	v_mov_b32_dpp v222, v158 row_ror:1 row_mask:0xf bank_mask:0xf
	v_mov_b32_dpp v223, v158 row_ror:2 row_mask:0xf bank_mask:0xf
	v_mov_b32_dpp v224, v159 row_ror:1 row_mask:0xf bank_mask:0xf
	v_mov_b32_dpp v225, v159 row_ror:2 row_mask:0xf bank_mask:0xf
	v_pk_mul_f32 v[154:155], v[154:155], v[204:205] op_sel_hi:[1,0]
	v_pk_mul_f32 v[152:153], v[152:153], v[204:205] op_sel_hi:[1,0]
	s_and_saveexec_b64 s[0:1], s[8:9]
	s_cbranch_execz .LBB0_928
	v_lshl_add_u64 v[196:197], s[24:25], 0, v[202:203]
	v_lshl_add_u64 v[194:195], s[38:39], 0, v[202:203]
	global_store_dwordx4 v[196:197], v[156:159], off
	global_store_dwordx4 v[194:195], v[152:155], off
